# prologue x->bf16 row loop: the eight loads of a row issued together with counted waits instead of one vmcnt(0) round trip per load
# baseline (speedup 1.0000x reference)
; __device__ __forceinline__ unsigned cvt_pk_bf16(float lo, float hi) { unsigned r; asm volatile("v_cvt_pk_bf16_f32 %0, %1, %2" : "=v"(r) : "v"(lo), "v"(hi)); return r; }
; __global__ void __launch_bounds__(NTHREADS, 2) fwd_megakernel(Args args) {
;     ...
;         for (int row = gw; row < S; row += NGW) {
;             const f32x4* xr = (const f32x4*)(x_in + (size_t)row * DM) + lane;
;             u32x2* xb = (u32x2*)(XB + (size_t)row * ALD) + lane; float ss = 0.f;
; #pragma unroll
;             for (int j = 0; j < 8; ++j) { const f32x4 v = xr[64 * j]; ss += (v.x * v.x + v.y * v.y) + (v.z * v.z + v.w * v.w);
;                 u32x2 w; w.x = cvt_pk_bf16(v.x, v.y); w.y = cvt_pk_bf16(v.z, v.w); xb[64 * j] = w; }
;             ss = wave_sum(ss);
;             if (lane < NPART) part[(size_t)row * NPART + lane] = (lane == 0) ? ss : 0.f;
;         }
.LBB0_26:
	v_add_co_u32_e32 v66, vcc, 0xfffff000, v4
	s_nop 1
	v_addc_co_u32_e32 v67, vcc, -1, v5, vcc
	s_waitcnt lgkmcnt(0)
	global_load_dwordx4 v[16:19], v[66:67], off offset:-3072
	global_load_dwordx4 v[20:23], v[66:67], off offset:-2048
	global_load_dwordx4 v[24:27], v[66:67], off offset:-1024
	global_load_dwordx4 v[28:31], v[4:5], off offset:-4096
	global_load_dwordx4 v[32:35], v[4:5], off offset:-3072
	global_load_dwordx4 v[36:39], v[4:5], off offset:-2048
	global_load_dwordx4 v[40:43], v[4:5], off offset:-1024
	global_load_dwordx4 v[44:47], v[4:5], off
	s_waitcnt vmcnt(7)
	v_cvt_pk_bf16_f32 v50, v16, v17
	v_cvt_pk_bf16_f32 v51, v18, v19
	global_store_dwordx2 v[6:7], v[50:51], off offset:-2048
	s_waitcnt vmcnt(7)
	v_cvt_pk_bf16_f32 v52, v20, v21
	v_cvt_pk_bf16_f32 v53, v22, v23
	global_store_dwordx2 v[6:7], v[52:53], off offset:-1536
	s_waitcnt vmcnt(7)
	v_cvt_pk_bf16_f32 v54, v24, v25
	v_cvt_pk_bf16_f32 v55, v26, v27
	global_store_dwordx2 v[6:7], v[54:55], off offset:-1024
	s_waitcnt vmcnt(7)
	v_cvt_pk_bf16_f32 v56, v28, v29
	v_cvt_pk_bf16_f32 v57, v30, v31
	global_store_dwordx2 v[6:7], v[56:57], off offset:-512
	s_waitcnt vmcnt(7)
	v_cvt_pk_bf16_f32 v58, v32, v33
	v_cvt_pk_bf16_f32 v59, v34, v35
	global_store_dwordx2 v[6:7], v[58:59], off
	s_waitcnt vmcnt(7)
	v_cvt_pk_bf16_f32 v60, v36, v37
	v_cvt_pk_bf16_f32 v61, v38, v39
	global_store_dwordx2 v[6:7], v[60:61], off offset:512
	s_waitcnt vmcnt(7)
	v_cvt_pk_bf16_f32 v62, v40, v41
	v_cvt_pk_bf16_f32 v63, v42, v43
	global_store_dwordx2 v[6:7], v[62:63], off offset:1024
	s_waitcnt vmcnt(7)
	v_cvt_pk_bf16_f32 v64, v44, v45
	v_cvt_pk_bf16_f32 v65, v46, v47
	global_store_dwordx2 v[6:7], v[64:65], off offset:1536
	v_cmp_lt_i32_e32 vcc, v10, v9
	v_mul_f32_e32 v17, v17, v17
	v_mul_f32_e32 v19, v19, v19
	v_fmac_f32_e32 v17, v16, v16
	v_fmac_f32_e32 v19, v18, v18
	v_add_f32_e32 v16, v17, v19
	v_mul_f32_e32 v17, v21, v21
	v_mul_f32_e32 v18, v23, v23
	v_fmac_f32_e32 v17, v20, v20
	v_fmac_f32_e32 v18, v22, v22
	v_add_f32_e32 v17, v17, v18
	v_add_f32_e32 v16, v16, v17
	v_mul_f32_e32 v17, v25, v25
	v_mul_f32_e32 v18, v27, v27
	v_fmac_f32_e32 v17, v24, v24
	v_fmac_f32_e32 v18, v26, v26
	v_add_f32_e32 v17, v17, v18
	v_add_f32_e32 v16, v16, v17
	v_mul_f32_e32 v17, v29, v29
	v_mul_f32_e32 v18, v31, v31
	v_fmac_f32_e32 v17, v28, v28
	v_fmac_f32_e32 v18, v30, v30
	v_add_f32_e32 v17, v17, v18
	v_add_f32_e32 v16, v16, v17
	v_mul_f32_e32 v17, v33, v33
	v_mul_f32_e32 v18, v35, v35
	v_fmac_f32_e32 v17, v32, v32
	v_fmac_f32_e32 v18, v34, v34
	v_add_f32_e32 v17, v17, v18
	v_add_f32_e32 v16, v16, v17
	v_mul_f32_e32 v17, v37, v37
	v_mul_f32_e32 v18, v39, v39
	v_fmac_f32_e32 v17, v36, v36
	v_fmac_f32_e32 v18, v38, v38
	v_add_f32_e32 v17, v17, v18
	v_add_f32_e32 v16, v16, v17
	v_mul_f32_e32 v17, v41, v41
	v_mul_f32_e32 v18, v43, v43
	v_fmac_f32_e32 v17, v40, v40
	v_fmac_f32_e32 v18, v42, v42
	v_add_f32_e32 v17, v17, v18
	v_add_f32_e32 v16, v16, v17
	v_mul_f32_e32 v17, v45, v45
	v_mul_f32_e32 v18, v47, v47
	v_fmac_f32_e32 v17, v44, v44
	v_fmac_f32_e32 v18, v46, v46
	v_cndmask_b32_e32 v48, v1, v10, vcc
	v_add_f32_e32 v17, v17, v18
	v_lshlrev_b32_e32 v48, 2, v48
	v_add_f32_e32 v16, v16, v17
	ds_bpermute_b32 v17, v48, v16
	v_cmp_lt_i32_e32 vcc, v11, v9
	s_waitcnt lgkmcnt(0)
	v_add_f32_e32 v16, v16, v17
	v_cndmask_b32_e32 v18, v1, v11, vcc
	v_lshlrev_b32_e32 v18, 2, v18
	ds_bpermute_b32 v17, v18, v16
	v_cmp_lt_i32_e32 vcc, v12, v9
	s_waitcnt lgkmcnt(0)
	v_add_f32_e32 v16, v16, v17
	v_cndmask_b32_e32 v18, v1, v12, vcc
	v_lshlrev_b32_e32 v18, 2, v18
	ds_bpermute_b32 v17, v18, v16
	v_cmp_lt_i32_e32 vcc, v13, v9
	s_waitcnt lgkmcnt(0)
	v_add_f32_e32 v16, v16, v17
	v_cndmask_b32_e32 v18, v1, v13, vcc
	v_lshlrev_b32_e32 v18, 2, v18
	ds_bpermute_b32 v17, v18, v16
	v_cmp_lt_i32_e32 vcc, v14, v9
	s_waitcnt lgkmcnt(0)
	v_add_f32_e32 v16, v16, v17
	v_cndmask_b32_e32 v18, v1, v14, vcc
	v_lshlrev_b32_e32 v18, 2, v18
	ds_bpermute_b32 v17, v18, v16
	v_cmp_lt_i32_e32 vcc, v15, v9
	s_waitcnt lgkmcnt(0)
	v_add_f32_e32 v16, v16, v17
	v_cndmask_b32_e32 v18, v1, v15, vcc
	v_lshlrev_b32_e32 v17, 2, v18
	ds_bpermute_b32 v17, v17, v16
	s_and_saveexec_b64 s[14:15], s[4:5]
	s_cbranch_execz .LBB0_25
	s_waitcnt lgkmcnt(0)
	v_add_f32_e32 v16, v16, v17
	v_cndmask_b32_e64 v16, 0, v16, s[6:7]
	global_store_dword v[2:3], v16, off
	s_branch .LBB0_25
